# no global barrier after prep: next-layer FFN weights published by a per-XCD write-back + ready counter; XCD pipelines run time-shifted (3 us per XCD once)
# speedup vs baseline: 1.0715x; 1.0125x over previous
; DI unsigned xb_ld(unsigned* p)              { return __hip_atomic_load(p, __ATOMIC_RELAXED, __HIP_MEMORY_SCOPE_AGENT); }
; DI unsigned xb_add(unsigned* p, unsigned v) { return __hip_atomic_fetch_add(p, v, __ATOMIC_RELAXED, __HIP_MEMORY_SCOPE_AGENT); }
; #define XB_SPIN(cond, bar) do { unsigned _sp = 0; while (cond) { __builtin_amdgcn_s_sleep(1); \
;     if ((++_sp & 255u) == 0u) { if (xb_ld(&(bar)[XB_TMO])) break; if (_sp > XB_SPIN_CAP) { atomicAdd(&(bar)[XB_TMO], 1u); break; } } } } while (0)
; DI void xcd_barrier(const XcdBarrier& b, const int gw) {
;     ...
;         const unsigned old = xb_add(&bar[XB_XSUB(b.x)], 1u);
;         const unsigned gen = old / nloc;
;         if (old + 1u == (gen + 1u) * nloc) {
;             __builtin_amdgcn_fence(__ATOMIC_RELEASE, "agent");
;             asm volatile("s_waitcnt vmcnt(0)" ::: "memory");
;             const unsigned og = xb_add(&bar[XB_TOP], 1u);
;             const unsigned tg = og / nx;
;             if (og + 1u == (tg + 1u) * nx) xb_add(&bar[XB_TOPGEN], 1u);
;             else XB_SPIN(xb_ld(&bar[XB_TOPGEN]) == tg, bar);
;             __builtin_amdgcn_fence(__ATOMIC_ACQUIRE, "agent");
;             xb_add(&bar[XB_XGEN(b.x)], 1u);
.LBB0_528:
	s_andn2_saveexec_b64 s[8:9], s[8:9]
	s_cbranch_execz .LBB0_548
	s_mov_b64 s[8:9], exec
	s_add_i32 s98, s36, -1
	s_lshr_b32 s98, 0x1ffffffe, s98
	s_bitcmp1_b32 s98, 0
	s_cbranch_scc0 .Lxb_global
	v_mov_b32_e32 v1, 0x20048
	ds_read_b32 v1, v1
	s_waitcnt lgkmcnt(0)
	v_readfirstlane_b32 s98, v1
	s_cmp_lg_u32 s98, 0
	s_cbranch_scc0 .Lxb_global
	s_add_i32 s98, s36, -1
	s_lshr_b32 s98, 0x81020, s98
	s_bitcmp1_b32 s98, 0
	s_cbranch_scc0 .LBB0_545
	buffer_wbl2 sc1
	s_waitcnt vmcnt(0)
	v_mov_b32_e32 v1, 0x2c0
	v_mov_b32_e32 v2, 1
	v_readlane_b32 s98, v254, 2
	v_readlane_b32 s99, v254, 3
	s_nop 4
	global_atomic_add v1, v2, s[98:99]
	s_branch .LBB0_545

; DI int obid() { int b = blockIdx.x; asm volatile("" : "+s"(b)); return b; }
; DI int ogrid() { int g = gridDim.x; asm volatile("" : "+s"(g)); return g; }
; DI int olane() { int l; asm volatile("v_mbcnt_lo_u32_b32 %0, -1, 0\n\tv_mbcnt_hi_u32_b32 %0, -1, %0" : "=v"(l)); return l; }
; DI unsigned xb_ld(unsigned* p)              { return __hip_atomic_load(p, __ATOMIC_RELAXED, __HIP_MEMORY_SCOPE_AGENT); }
; DI unsigned xb_add(unsigned* p, unsigned v) { return __hip_atomic_fetch_add(p, v, __ATOMIC_RELAXED, __HIP_MEMORY_SCOPE_AGENT); }
; DI void xcd_barrier(const XcdBarrier& b, const int gw) {
;     asm volatile("s_waitcnt vmcnt(0)" ::: "memory");
;     __syncthreads();
;     if (gw == 0 && olane() == 0) {
;         unsigned* bar = b.bar;
;         __builtin_amdgcn_s_waitcnt(0);
;         unsigned nloc = b.st[0], nx = b.st[1];
;         if (nloc == 0u) { xcd_barrier_complete(bar, b.x, nloc, nx); b.st[0] = nloc; b.st[1] = nx; }
;         const unsigned old = xb_add(&bar[XB_XSUB(b.x)], 1u);
;         const unsigned gen = old / nloc;
;         if (old + 1u == (gen + 1u) * nloc) {
;             __builtin_amdgcn_fence(__ATOMIC_RELEASE, "agent");
;             asm volatile("s_waitcnt vmcnt(0)" ::: "memory");
;             const unsigned og = xb_add(&bar[XB_TOP], 1u);
;             const unsigned tg = og / nx;
;             if (og + 1u == (tg + 1u) * nx) xb_add(&bar[XB_TOPGEN], 1u);
;             else XB_SPIN(xb_ld(&bar[XB_TOPGEN]) == tg, bar);
;             __builtin_amdgcn_fence(__ATOMIC_ACQUIRE, "agent");
;             xb_add(&bar[XB_XGEN(b.x)], 1u);
;             asm volatile("s_waitcnt vmcnt(0)" ::: "memory");
;         } else {
;             XB_SPIN(xb_ld(&bar[XB_XGEN(b.x)]) == gen, bar);
;             __builtin_amdgcn_fence(__ATOMIC_ACQUIRE, "agent");
;             asm volatile("s_waitcnt vmcnt(0)" ::: "memory");
;         }
;     }
;     __syncthreads();
; __global__ void __launch_bounds__(NTHREADS) fwd_kernel(Params p) {
;     ...
;                 gemm_phase<EPI_FFN_IN>(HB, (const bf16_t*)(ws + OFF_FFN_IN_T) + (size_t)L * FFN_IN * DM, DM, FFN_IN, q, j, lds);
;                 if (L < 3) { const int rem_ = ((M_TOK / 256) * (FFN_IN / 256)) % ogrid();
;                     if (obid() >= rem_) convert_layer_weights(q, L + 1, obid() - rem_, ogrid() - rem_, lds, 2); }
.LBB0_548:
	s_or_b64 exec, exec, s[4:5]
	s_add_i32 s98, s36, -1
	s_lshr_b32 s99, 0x2040800, s98
	s_bitcmp1_b32 s99, 0
	s_cbranch_scc0 .Lrdy_done
	v_mov_b32_e32 v1, 0x20048
	ds_read_b32 v1, v1
	s_waitcnt lgkmcnt(0)
	v_readfirstlane_b32 s99, v1
	s_cmp_lg_u32 s99, 0
	s_cbranch_scc0 .Lrdy_done
	v_readlane_b32 s99, v255, 6
	v_readlane_b32 vcc_lo, v254, 2
	v_readlane_b32 vcc_hi, v254, 3
	v_mov_b32_e32 v1, 0x2c0
	s_lshl_b32 s99, s99, 3
	s_nop 3
.Lrdy_poll:
	global_load_dword v2, v1, vcc sc1
	s_waitcnt vmcnt(0)
	v_readfirstlane_b32 s98, v2
	s_cmp_ge_u32 s98, s99
	s_cbranch_scc1 .Lrdy_done
	s_sleep 1
	s_branch .Lrdy_poll
.Lrdy_done:
.LBB0_549:
	s_mov_b64 s[4:5], 0
	s_waitcnt lgkmcnt(0)
	s_barrier
	s_add_i32 s98, s36, -1
	s_lshr_b32 s98, 0x1ffffffe, s98
	s_bitcmp1_b32 s98, 0
	s_cbranch_scc1 .Lnostag
	s_and_b32 s98, s2, 7
	s_cmp_eq_u32 s98, 0
	s_cbranch_scc1 .Lnostag
.Lstag:
	s_sleep 96
	s_sub_u32 s98, s98, 1
	s_cmp_lg_u32 s98, 0
	s_cbranch_scc1 .Lstag
.Lnostag:
.LBB0_550:
	s_and_b64 vcc, exec, s[4:5]
	s_cbranch_vccnz .LBB0_551
	s_getpc_b64 s[98:99]
